# adaLN norm phases (norm1, norm2): gain/scale/shift loads of column chunks 1..3 of each row issued together with chunk 0's into spare registers; waits re-derived as counted waits that no longer cover t
# speedup vs baseline: 1.0195x; 1.0195x over previous
.LBB0_328:
	s_or_b64 exec, exec, s[10:11]
	s_waitcnt vmcnt(3)
	v_mov_b32_e32 v70, v47
	s_waitcnt vmcnt(2)
	v_mov_b32_e32 v71, v43
	v_mov_b32_e32 v52, v46
	v_mov_b32_e32 v53, v42
	v_pk_mul_f32 v[70:71], v[70:71], v[70:71]
	s_waitcnt vmcnt(1)
	v_mov_b32_e32 v76, v39
	v_pk_fma_f32 v[52:53], v[52:53], v[52:53], v[70:71]
	v_mov_b32_e32 v70, v48
	v_mov_b32_e32 v71, v44
	v_pk_fma_f32 v[52:53], v[70:71], v[70:71], v[52:53]
	v_mov_b32_e32 v70, v49
	v_mov_b32_e32 v71, v45
	s_waitcnt vmcnt(0)
	v_mov_b32_e32 v77, v35
	v_pk_fma_f32 v[52:53], v[70:71], v[70:71], v[52:53]
	v_mov_b32_e32 v70, v38
	v_mov_b32_e32 v71, v34
	v_pk_mul_f32 v[76:77], v[76:77], v[76:77]
	v_add_f32_e32 v0, v52, v53
	v_pk_fma_f32 v[70:71], v[70:71], v[70:71], v[76:77]
	v_mov_b32_e32 v76, v40
	v_mov_b32_e32 v77, v36
	v_pk_fma_f32 v[70:71], v[76:77], v[76:77], v[70:71]
	v_mov_b32_e32 v76, v41
	v_mov_b32_e32 v77, v37
	v_pk_fma_f32 v[70:71], v[76:77], v[76:77], v[70:71]
	s_mov_b32 s3, 0x800000
	v_add_f32_e32 v0, v0, v70
	v_add_f32_e32 v0, v0, v71
	ds_bpermute_b32 v52, v55, v0
	v_lshlrev_b64 v[78:79], 11, v[50:51]
	v_lshl_add_u64 v[78:79], v[66:67], 0, v[78:79]
	s_waitcnt lgkmcnt(0)
	v_add_f32_e32 v0, v0, v52
	ds_bpermute_b32 v52, v59, v0
	s_waitcnt lgkmcnt(0)
	v_add_f32_e32 v0, v0, v52
	ds_bpermute_b32 v52, v61, v0
	s_waitcnt lgkmcnt(0)
	v_add_f32_e32 v0, v0, v52
	ds_bpermute_b32 v52, v63, v0
	s_waitcnt lgkmcnt(0)
	v_add_f32_e32 v0, v0, v52
	ds_bpermute_b32 v52, v75, v0
	s_waitcnt lgkmcnt(0)
	v_add_f32_e32 v0, v0, v52
	ds_bpermute_b32 v52, v82, v0
	s_waitcnt lgkmcnt(0)
	v_add_f32_e32 v0, v0, v52
	v_fmamk_f32 v0, v0, 0x3a800000, v162
	v_cmp_gt_f32_e32 vcc, s3, v0
	v_mul_f32_e32 v52, 0x4b800000, v0
	s_movk_i32 s3, 0x1fff
	v_cndmask_b32_e32 v0, v0, v52, vcc
	v_rsq_f32_e32 v0, v0
	s_nop 0
	v_mul_f32_e32 v52, 0x45800000, v0
	v_cndmask_b32_e32 v74, v0, v52, vcc
	v_lshrrev_b32_e32 v0, 11, v83
	v_add_u32_e32 v0, 1, v0
	v_cmp_lt_i32_e32 vcc, s3, v50
	v_mov_b64_e32 v[52:53], s[6:7]
	v_pk_mul_f32 v[48:49], v[48:49], v[74:75] op_sel_hi:[1,0]
	v_cndmask_b32_e32 v0, 0, v0, vcc
	v_mad_u64_u32 v[70:71], s[10:11], v0, s33, v[52:53]
	s_mov_b64 s[10:11], 0x1000
	s_nop 0
	v_lshl_add_u64 v[76:77], v[70:71], 0, s[10:11]
	v_lshlrev_b32_e32 v0, 2, v54
	v_lshl_add_u64 v[80:81], v[70:71], 0, v[0:1]
	v_lshl_add_u64 v[70:71], v[76:77], 0, v[0:1]
	global_load_dwordx4 v[50:53], v[56:57], off
	global_load_dwordx4 v[90:93], v[70:71], off
	global_load_dwordx4 v[86:89], v[80:81], off
	v_lshl_add_u64 v[134:135], v[76:77], 0, v[0:1]
	global_load_dwordx4 v[98:101], v[56:57], off offset:1024
	global_load_dwordx4 v[102:105], v[80:81], off offset:1024
	global_load_dwordx4 v[106:109], v[134:135], off offset:1024
	global_load_dwordx4 v[110:113], v[56:57], off offset:2048
	global_load_dwordx4 v[114:117], v[80:81], off offset:2048
	global_load_dwordx4 v[118:121], v[134:135], off offset:2048
	global_load_dwordx4 v[122:125], v[56:57], off offset:3072
	global_load_dwordx4 v[126:129], v[80:81], off offset:3072
	global_load_dwordx4 v[130:133], v[134:135], off offset:3072
	v_pk_mul_f32 v[46:47], v[46:47], v[74:75] op_sel_hi:[1,0]
	v_lshlrev_b32_e32 v70, 2, v58
	v_mov_b32_e32 v71, v1
	v_pk_mul_f32 v[44:45], v[44:45], v[74:75] op_sel_hi:[1,0]
	v_pk_mul_f32 v[42:43], v[42:43], v[74:75] op_sel_hi:[1,0]
	v_pk_mul_f32 v[40:41], v[40:41], v[74:75] op_sel_hi:[1,0]
	v_pk_mul_f32 v[38:39], v[38:39], v[74:75] op_sel_hi:[1,0]
	v_pk_mul_f32 v[36:37], v[36:37], v[74:75] op_sel_hi:[1,0]
	v_pk_mul_f32 v[34:35], v[34:35], v[74:75] op_sel_hi:[1,0]
	v_cmp_gt_i32_e32 vcc, s33, v72
	s_waitcnt vmcnt(11)
	v_pk_mul_f32 v[46:47], v[50:51], v[46:47]
	v_pk_mul_f32 v[48:49], v[52:53], v[48:49]
	s_waitcnt vmcnt(10)
	v_pk_add_f32 v[50:51], v[92:93], 1.0 op_sel_hi:[1,0]
	v_pk_add_f32 v[52:53], v[90:91], 1.0 op_sel_hi:[1,0]
	s_waitcnt vmcnt(9)
	v_pk_fma_f32 v[48:49], v[50:51], v[48:49], v[88:89]
	v_pk_fma_f32 v[46:47], v[52:53], v[46:47], v[86:87]
	v_cvt_pk_bf16_f32 v46, v46, v47
	v_cvt_pk_bf16_f32 v47, v48, v49
	global_store_dwordx2 v[78:79], v[46:47], off
	s_waitcnt vmcnt(9)
	v_pk_mul_f32 v[42:43], v[98:99], v[42:43]
	v_pk_mul_f32 v[44:45], v[100:101], v[44:45]
	s_waitcnt vmcnt(7)
	v_pk_add_f32 v[50:51], v[108:109], 1.0 op_sel_hi:[1,0]
	v_pk_add_f32 v[52:53], v[106:107], 1.0 op_sel_hi:[1,0]
	v_pk_fma_f32 v[44:45], v[50:51], v[44:45], v[104:105]
	v_pk_fma_f32 v[42:43], v[52:53], v[42:43], v[102:103]
	s_nop 0
	v_cvt_pk_bf16_f32 v42, v42, v43
	v_cvt_pk_bf16_f32 v43, v44, v45
	global_store_dwordx2 v[78:79], v[42:43], off offset:512
	v_lshlrev_b32_e32 v42, 2, v60
	v_mov_b32_e32 v43, v1
	s_waitcnt vmcnt(7)
	v_pk_mul_f32 v[38:39], v[110:111], v[38:39]
	v_pk_mul_f32 v[40:41], v[112:113], v[40:41]
	s_waitcnt vmcnt(5)
	v_pk_add_f32 v[44:45], v[120:121], 1.0 op_sel_hi:[1,0]
	v_pk_add_f32 v[46:47], v[118:119], 1.0 op_sel_hi:[1,0]
	v_pk_fma_f32 v[40:41], v[44:45], v[40:41], v[116:117]
	v_pk_fma_f32 v[38:39], v[46:47], v[38:39], v[114:115]
	v_lshlrev_b32_e32 v44, 2, v62
	v_cvt_pk_bf16_f32 v38, v38, v39
	v_cvt_pk_bf16_f32 v39, v40, v41
	v_mov_b32_e32 v45, v1
	global_store_dwordx2 v[78:79], v[38:39], off offset:1024
	s_waitcnt vmcnt(5)
	v_pk_mul_f32 v[34:35], v[34:35], v[122:123]
	v_pk_mul_f32 v[36:37], v[36:37], v[124:125]
	s_waitcnt vmcnt(3)
	v_pk_add_f32 v[38:39], v[132:133], 1.0 op_sel_hi:[1,0]
	v_pk_add_f32 v[40:41], v[130:131], 1.0 op_sel_hi:[1,0]
	v_pk_fma_f32 v[36:37], v[36:37], v[38:39], v[128:129]
	v_pk_fma_f32 v[34:35], v[34:35], v[40:41], v[126:127]
	s_nop 0
	v_cvt_pk_bf16_f32 v34, v34, v35
	v_cvt_pk_bf16_f32 v35, v36, v37
	global_store_dwordx2 v[78:79], v[34:35], off offset:1536
	s_and_saveexec_b64 s[10:11], vcc
	s_cbranch_execz .LBB0_330
	v_mov_b32_e32 v36, v27
	v_mov_b32_e32 v37, v31
	v_mov_b32_e32 v34, v26
	v_mov_b32_e32 v35, v30
	v_pk_mul_f32 v[36:37], v[36:37], v[36:37]
	v_mov_b32_e32 v38, v19
	v_pk_fma_f32 v[34:35], v[34:35], v[34:35], v[36:37]
	v_mov_b32_e32 v36, v28
	v_mov_b32_e32 v37, v32
	v_pk_fma_f32 v[34:35], v[36:37], v[36:37], v[34:35]
	v_mov_b32_e32 v36, v29
	v_mov_b32_e32 v37, v33
	v_mov_b32_e32 v39, v23
	v_pk_fma_f32 v[34:35], v[36:37], v[36:37], v[34:35]
	v_mov_b32_e32 v36, v18
	v_mov_b32_e32 v37, v22
	v_pk_mul_f32 v[38:39], v[38:39], v[38:39]
	v_add_f32_e32 v34, v34, v35
	v_pk_fma_f32 v[36:37], v[36:37], v[36:37], v[38:39]
	v_mov_b32_e32 v38, v20
	v_mov_b32_e32 v39, v24
	v_pk_fma_f32 v[36:37], v[38:39], v[38:39], v[36:37]
	v_mov_b32_e32 v38, v21
	v_mov_b32_e32 v39, v25
	v_pk_fma_f32 v[36:37], v[38:39], v[38:39], v[36:37]
	s_mov_b32 s3, 0x800000
	v_add_f32_e32 v34, v37, v34
	v_add_f32_e32 v34, v36, v34
	ds_bpermute_b32 v35, v55, v34
	v_mov_b64_e32 v[36:37], s[6:7]
	global_load_dwordx4 v[50:53], v[56:57], off
	v_lshlrev_b64 v[48:49], 11, v[72:73]
	s_waitcnt lgkmcnt(0)
	v_add_f32_e32 v34, v34, v35
	ds_bpermute_b32 v35, v59, v34
	s_waitcnt lgkmcnt(0)
	v_add_f32_e32 v34, v34, v35
	ds_bpermute_b32 v35, v61, v34
	s_waitcnt lgkmcnt(0)
	v_add_f32_e32 v34, v34, v35
	ds_bpermute_b32 v35, v63, v34
	s_waitcnt lgkmcnt(0)
	v_add_f32_e32 v34, v34, v35
	ds_bpermute_b32 v35, v75, v34
	s_waitcnt lgkmcnt(0)
	v_add_f32_e32 v34, v34, v35
	ds_bpermute_b32 v35, v82, v34
	s_waitcnt lgkmcnt(0)
	v_add_f32_e32 v34, v34, v35
	v_fmamk_f32 v34, v34, 0x3a800000, v162
	v_cmp_gt_f32_e32 vcc, s3, v34
	v_mul_f32_e32 v35, 0x4b800000, v34
	s_movk_i32 s3, 0x1fff
	v_cndmask_b32_e32 v34, v34, v35, vcc
	v_rsq_f32_e32 v34, v34
	s_nop 0
	v_mul_f32_e32 v35, 0x45800000, v34
	v_cndmask_b32_e32 v34, v34, v35, vcc
	v_lshrrev_b32_e32 v35, 11, v85
	v_add_u32_e32 v35, 1, v35
	v_cmp_lt_i32_e32 vcc, s3, v72
	v_lshl_add_u64 v[72:73], v[66:67], 0, v[48:49]
	s_nop 0
	v_cndmask_b32_e32 v35, 0, v35, vcc
	v_mad_u64_u32 v[38:39], s[12:13], v35, s33, v[36:37]
	s_mov_b64 s[12:13], 0x1000
	s_nop 0
	v_lshl_add_u64 v[36:37], v[38:39], 0, s[12:13]
	v_lshl_add_u64 v[40:41], v[36:37], 0, v[0:1]
	v_lshl_add_u64 v[38:39], v[38:39], 0, v[0:1]
	global_load_dwordx4 v[86:89], v[40:41], off
	global_load_dwordx4 v[76:79], v[38:39], off
	v_lshl_add_u64 v[134:135], v[36:37], 0, v[0:1]
	global_load_dwordx4 v[98:101], v[56:57], off offset:1024
	global_load_dwordx4 v[102:105], v[38:39], off offset:1024
	global_load_dwordx4 v[106:109], v[134:135], off offset:1024
	global_load_dwordx4 v[110:113], v[56:57], off offset:2048
	global_load_dwordx4 v[114:117], v[38:39], off offset:2048
	global_load_dwordx4 v[118:121], v[134:135], off offset:2048
	global_load_dwordx4 v[122:125], v[56:57], off offset:3072
	global_load_dwordx4 v[126:129], v[38:39], off offset:3072
	global_load_dwordx4 v[130:133], v[134:135], off offset:3072
	v_pk_mul_f32 v[40:41], v[32:33], v[34:35] op_sel_hi:[1,0]
	v_pk_mul_f32 v[46:47], v[30:31], v[34:35] op_sel_hi:[1,0]
	v_pk_mul_f32 v[80:81], v[26:27], v[34:35] op_sel_hi:[1,0]
	s_waitcnt vmcnt(11)
	v_pk_mul_f32 v[46:47], v[50:51], v[46:47]
	v_pk_mul_f32 v[40:41], v[52:53], v[40:41]
	s_waitcnt vmcnt(10)
	v_pk_add_f32 v[50:51], v[88:89], 1.0 op_sel_hi:[1,0]
	v_pk_add_f32 v[52:53], v[86:87], 1.0 op_sel_hi:[1,0]
	s_waitcnt vmcnt(9)
	v_pk_fma_f32 v[40:41], v[50:51], v[40:41], v[78:79]
	v_pk_fma_f32 v[46:47], v[52:53], v[46:47], v[76:77]
	s_nop 0
	v_cvt_pk_bf16_f32 v46, v46, v47
	v_cvt_pk_bf16_f32 v47, v40, v41
	global_store_dwordx2 v[72:73], v[46:47], off
	v_pk_mul_f32 v[40:41], v[28:29], v[34:35] op_sel_hi:[1,0]
	s_waitcnt vmcnt(9)
	v_pk_mul_f32 v[46:47], v[98:99], v[80:81]
	v_pk_mul_f32 v[40:41], v[100:101], v[40:41]
	s_waitcnt vmcnt(7)
	v_pk_add_f32 v[48:49], v[108:109], 1.0 op_sel_hi:[1,0]
	v_pk_add_f32 v[76:77], v[106:107], 1.0 op_sel_hi:[1,0]
	v_pk_fma_f32 v[40:41], v[48:49], v[40:41], v[104:105]
	v_pk_fma_f32 v[46:47], v[76:77], v[46:47], v[102:103]
	v_pk_mul_f32 v[80:81], v[22:23], v[34:35] op_sel_hi:[1,0]
	v_cvt_pk_bf16_f32 v46, v46, v47
	v_cvt_pk_bf16_f32 v47, v40, v41
	global_store_dwordx2 v[72:73], v[46:47], off offset:512
	v_pk_mul_f32 v[40:41], v[24:25], v[34:35] op_sel_hi:[1,0]
	s_waitcnt vmcnt(7)
	v_pk_mul_f32 v[46:47], v[110:111], v[80:81]
	v_pk_mul_f32 v[40:41], v[112:113], v[40:41]
	s_waitcnt vmcnt(5)
	v_pk_add_f32 v[48:49], v[120:121], 1.0 op_sel_hi:[1,0]
	v_pk_add_f32 v[76:77], v[118:119], 1.0 op_sel_hi:[1,0]
	v_pk_fma_f32 v[40:41], v[48:49], v[40:41], v[116:117]
	v_pk_fma_f32 v[46:47], v[76:77], v[46:47], v[114:115]
	s_nop 0
	v_cvt_pk_bf16_f32 v46, v46, v47
	v_cvt_pk_bf16_f32 v47, v40, v41
	global_store_dwordx2 v[72:73], v[46:47], off offset:1024
	v_pk_mul_f32 v[36:37], v[20:21], v[34:35] op_sel_hi:[1,0]
	v_pk_mul_f32 v[34:35], v[18:19], v[34:35] op_sel_hi:[1,0]
	s_waitcnt vmcnt(5)
	v_pk_mul_f32 v[36:37], v[36:37], v[124:125]
	v_pk_mul_f32 v[34:35], v[34:35], v[122:123]
	s_waitcnt vmcnt(3)
	v_pk_add_f32 v[46:47], v[132:133], 1.0 op_sel_hi:[1,0]
	v_pk_add_f32 v[48:49], v[130:131], 1.0 op_sel_hi:[1,0]
	v_pk_fma_f32 v[36:37], v[36:37], v[46:47], v[128:129]
	v_pk_fma_f32 v[34:35], v[34:35], v[48:49], v[126:127]
	s_nop 0
	v_cvt_pk_bf16_f32 v34, v34, v35
	v_cvt_pk_bf16_f32 v35, v36, v37
	global_store_dwordx2 v[72:73], v[34:35], off offset:1536
.LBB0_330:
	s_or_b64 exec, exec, s[10:11]
	v_cmp_gt_i32_e32 vcc, s33, v68
	s_and_saveexec_b64 s[10:11], vcc
	s_cbranch_execz .LBB0_323
	v_mov_b32_e32 v36, v11
	v_mov_b32_e32 v37, v15
	v_mov_b32_e32 v34, v10
	v_mov_b32_e32 v35, v14
	v_pk_mul_f32 v[36:37], v[36:37], v[36:37]
	s_mov_b32 s3, 0x800000
	v_pk_fma_f32 v[34:35], v[34:35], v[34:35], v[36:37]
	v_mov_b32_e32 v36, v12
	v_mov_b32_e32 v37, v16
	v_pk_fma_f32 v[34:35], v[36:37], v[36:37], v[34:35]
	v_mov_b32_e32 v36, v13
	v_mov_b32_e32 v37, v17
	v_pk_fma_f32 v[34:35], v[36:37], v[36:37], v[34:35]
	v_mov_b32_e32 v36, v3
	v_mov_b32_e32 v37, v7
	v_add_f32_e32 v38, v34, v35
	v_mov_b32_e32 v34, v2
	v_mov_b32_e32 v35, v6
	v_pk_mul_f32 v[36:37], v[36:37], v[36:37]
	v_lshlrev_b64 v[50:51], 11, v[68:69]
	v_pk_fma_f32 v[34:35], v[34:35], v[34:35], v[36:37]
	v_mov_b32_e32 v36, v4
	v_mov_b32_e32 v37, v8
	v_pk_fma_f32 v[34:35], v[36:37], v[36:37], v[34:35]
	v_mov_b32_e32 v36, v5
	v_mov_b32_e32 v37, v9
	v_pk_fma_f32 v[34:35], v[36:37], v[36:37], v[34:35]
	v_lshl_add_u64 v[50:51], v[66:67], 0, v[50:51]
	v_add_f32_e32 v35, v35, v38
	v_add_f32_e32 v34, v34, v35
	ds_bpermute_b32 v35, v55, v34
	v_mov_b32_e32 v71, v1
	v_mov_b32_e32 v43, v1
	v_mov_b32_e32 v45, v1
	s_waitcnt lgkmcnt(0)
	v_add_f32_e32 v34, v34, v35
	ds_bpermute_b32 v35, v59, v34
	s_waitcnt lgkmcnt(0)
	v_add_f32_e32 v34, v34, v35
	ds_bpermute_b32 v35, v61, v34
	s_waitcnt lgkmcnt(0)
	v_add_f32_e32 v34, v34, v35
	ds_bpermute_b32 v35, v63, v34
	s_waitcnt lgkmcnt(0)
	v_add_f32_e32 v34, v34, v35
	ds_bpermute_b32 v35, v75, v34
	s_waitcnt lgkmcnt(0)
	v_add_f32_e32 v34, v34, v35
	ds_bpermute_b32 v35, v82, v34
	s_waitcnt lgkmcnt(0)
	v_add_f32_e32 v34, v34, v35
	v_fmamk_f32 v34, v34, 0x3a800000, v162
	v_cmp_gt_f32_e32 vcc, s3, v34
	v_mul_f32_e32 v35, 0x4b800000, v34
	s_movk_i32 s3, 0x1fff
	v_cndmask_b32_e32 v34, v34, v35, vcc
	v_rsq_f32_e32 v34, v34
	s_nop 0
	v_mul_f32_e32 v35, 0x45800000, v34
	v_cndmask_b32_e32 v46, v34, v35, vcc
	v_lshrrev_b32_e32 v34, 11, v84
	v_add_u32_e32 v34, 1, v34
	v_cmp_lt_i32_e32 vcc, s3, v68
	v_pk_mul_f32 v[72:73], v[14:15], v[46:47] op_sel_hi:[1,0]
	s_nop 0
	v_cndmask_b32_e32 v36, 0, v34, vcc
	v_mov_b64_e32 v[34:35], s[6:7]
	v_mad_u64_u32 v[38:39], s[12:13], v36, s33, v[34:35]
	s_mov_b64 s[12:13], 0x1000
	s_nop 0
	v_lshl_add_u64 v[48:49], v[38:39], 0, s[12:13]
	v_lshl_add_u64 v[68:69], v[48:49], 0, v[0:1]
	global_load_dwordx4 v[34:37], v[56:57], off
	v_lshl_add_u64 v[52:53], v[38:39], 0, v[0:1]
	global_load_dwordx4 v[76:79], v[68:69], off
	global_load_dwordx4 v[38:41], v[52:53], off
	v_lshl_add_u64 v[134:135], v[48:49], 0, v[0:1]
	global_load_dwordx4 v[98:101], v[56:57], off offset:1024
	global_load_dwordx4 v[102:105], v[52:53], off offset:1024
	global_load_dwordx4 v[106:109], v[134:135], off offset:1024
	global_load_dwordx4 v[110:113], v[56:57], off offset:2048
	global_load_dwordx4 v[114:117], v[52:53], off offset:2048
	global_load_dwordx4 v[118:121], v[134:135], off offset:2048
	global_load_dwordx4 v[122:125], v[56:57], off offset:3072
	global_load_dwordx4 v[126:129], v[52:53], off offset:3072
	global_load_dwordx4 v[130:133], v[134:135], off offset:3072
	v_pk_mul_f32 v[68:69], v[16:17], v[46:47] op_sel_hi:[1,0]
	s_waitcnt vmcnt(11)
	v_pk_mul_f32 v[34:35], v[34:35], v[72:73]
	v_pk_mul_f32 v[36:37], v[36:37], v[68:69]
	s_waitcnt vmcnt(10)
	v_pk_add_f32 v[68:69], v[78:79], 1.0 op_sel_hi:[1,0]
	v_pk_add_f32 v[72:73], v[76:77], 1.0 op_sel_hi:[1,0]
	s_waitcnt vmcnt(9)
	v_pk_fma_f32 v[36:37], v[68:69], v[36:37], v[40:41]
	v_pk_fma_f32 v[34:35], v[72:73], v[34:35], v[38:39]
	v_cvt_pk_bf16_f32 v34, v34, v35
	v_cvt_pk_bf16_f32 v35, v36, v37
	global_store_dwordx2 v[50:51], v[34:35], off
	v_pk_mul_f32 v[72:73], v[12:13], v[46:47] op_sel_hi:[1,0]
	v_pk_mul_f32 v[76:77], v[10:11], v[46:47] op_sel_hi:[1,0]
	s_waitcnt vmcnt(9)
	v_pk_mul_f32 v[40:41], v[100:101], v[72:73]
	v_pk_mul_f32 v[38:39], v[98:99], v[76:77]
	v_pk_mul_f32 v[72:73], v[6:7], v[46:47] op_sel_hi:[1,0]
	s_waitcnt vmcnt(7)
	v_pk_add_f32 v[70:71], v[108:109], 1.0 op_sel_hi:[1,0]
	v_pk_add_f32 v[68:69], v[106:107], 1.0 op_sel_hi:[1,0]
	v_pk_fma_f32 v[36:37], v[70:71], v[40:41], v[104:105]
	v_pk_fma_f32 v[34:35], v[68:69], v[38:39], v[102:103]
	s_nop 0
	v_cvt_pk_bf16_f32 v34, v34, v35
	v_cvt_pk_bf16_f32 v35, v36, v37
	global_store_dwordx2 v[50:51], v[34:35], off offset:512
	v_pk_mul_f32 v[42:43], v[8:9], v[46:47] op_sel_hi:[1,0]
	s_waitcnt vmcnt(7)
	v_pk_mul_f32 v[34:35], v[110:111], v[72:73]
	v_pk_mul_f32 v[36:37], v[112:113], v[42:43]
	s_waitcnt vmcnt(5)
	v_pk_add_f32 v[42:43], v[120:121], 1.0 op_sel_hi:[1,0]
	v_pk_add_f32 v[68:69], v[118:119], 1.0 op_sel_hi:[1,0]
	v_pk_fma_f32 v[36:37], v[42:43], v[36:37], v[116:117]
	v_pk_fma_f32 v[34:35], v[68:69], v[34:35], v[114:115]
	v_cvt_pk_bf16_f32 v34, v34, v35
	v_cvt_pk_bf16_f32 v35, v36, v37
	global_store_dwordx2 v[50:51], v[34:35], off offset:1024
	v_pk_mul_f32 v[48:49], v[4:5], v[46:47] op_sel_hi:[1,0]
	v_pk_mul_f32 v[46:47], v[2:3], v[46:47] op_sel_hi:[1,0]
	s_waitcnt vmcnt(5)
	v_pk_mul_f32 v[36:37], v[48:49], v[124:125]
	v_pk_mul_f32 v[34:35], v[46:47], v[122:123]
	s_waitcnt vmcnt(3)
	v_pk_add_f32 v[44:45], v[132:133], 1.0 op_sel_hi:[1,0]
	v_pk_add_f32 v[42:43], v[130:131], 1.0 op_sel_hi:[1,0]
	v_pk_fma_f32 v[36:37], v[36:37], v[44:45], v[128:129]
	v_pk_fma_f32 v[34:35], v[34:35], v[42:43], v[126:127]
	s_nop 0
	v_cvt_pk_bf16_f32 v34, v34, v35
	v_cvt_pk_bf16_f32 v35, v36, v37
	global_store_dwordx2 v[50:51], v[34:35], off offset:1536
	s_branch .LBB0_323

.LBB0_1292:
	s_or_b64 exec, exec, s[20:21]
	v_lshrrev_b32_e32 v63, 11, v62
	v_add_u32_e32 v63, 1, v63
	v_cmp_lt_i32_e32 vcc, s3, v72
	v_mov_b64_e32 v[76:77], s[16:17]
	s_waitcnt vmcnt(3)
	v_mov_b32_e32 v94, v47
	v_cndmask_b32_e32 v63, 0, v63, vcc
	v_mad_u64_u32 v[84:85], s[4:5], v63, s33, v[76:77]
	s_mov_b64 s[4:5], 0x1000
	s_nop 0
	v_lshl_add_u64 v[88:89], v[84:85], 0, s[4:5]
	v_lshl_add_u64 v[80:81], v[88:89], 0, v[0:1]
	global_load_dwordx4 v[76:79], v[52:53], off
	v_lshl_add_u64 v[90:91], v[84:85], 0, v[0:1]
	global_load_dwordx4 v[80:83], v[80:81], off
	s_waitcnt vmcnt(4)
	v_mov_b32_e32 v95, v43
	global_load_dwordx4 v[84:87], v[90:91], off
	v_lshl_add_u64 v[134:135], v[88:89], 0, v[0:1]
	global_load_dwordx4 v[98:101], v[52:53], off offset:1024
	global_load_dwordx4 v[102:105], v[134:135], off offset:1024
	global_load_dwordx4 v[106:109], v[90:91], off offset:1024
	global_load_dwordx4 v[110:113], v[52:53], off offset:2048
	global_load_dwordx4 v[114:117], v[134:135], off offset:2048
	global_load_dwordx4 v[118:121], v[90:91], off offset:2048
	global_load_dwordx4 v[122:125], v[52:53], off offset:3072
	global_load_dwordx4 v[126:129], v[134:135], off offset:3072
	global_load_dwordx4 v[130:133], v[90:91], off offset:3072
	v_mov_b32_e32 v92, v46
	v_mov_b32_e32 v93, v42
	v_pk_mul_f32 v[94:95], v[94:95], v[94:95]
	s_waitcnt vmcnt(13)
	v_mov_b32_e32 v96, v39
	v_pk_fma_f32 v[92:93], v[92:93], v[92:93], v[94:95]
	v_mov_b32_e32 v94, v48
	v_mov_b32_e32 v95, v44
	v_pk_fma_f32 v[92:93], v[94:95], v[94:95], v[92:93]
	v_mov_b32_e32 v94, v49
	v_mov_b32_e32 v95, v45
	s_waitcnt vmcnt(12)
	v_mov_b32_e32 v97, v35
	v_pk_fma_f32 v[92:93], v[94:95], v[94:95], v[92:93]
	v_mov_b32_e32 v94, v38
	v_mov_b32_e32 v95, v34
	v_pk_mul_f32 v[96:97], v[96:97], v[96:97]
	v_add_f32_e32 v63, v92, v93
	v_pk_fma_f32 v[94:95], v[94:95], v[94:95], v[96:97]
	v_mov_b32_e32 v96, v40
	v_mov_b32_e32 v97, v36
	v_pk_fma_f32 v[94:95], v[96:97], v[96:97], v[94:95]
	v_mov_b32_e32 v96, v41
	v_mov_b32_e32 v97, v37
	v_pk_fma_f32 v[94:95], v[96:97], v[96:97], v[94:95]
	s_mov_b32 s3, 0x800000
	v_add_f32_e32 v63, v63, v94
	v_add_f32_e32 v63, v63, v95
	ds_bpermute_b32 v65, v51, v63
	v_lshlrev_b64 v[92:93], 11, v[72:73]
	v_lshl_add_u64 v[92:93], v[60:61], 0, v[92:93]
	v_lshlrev_b32_e32 v72, 2, v54
	v_mov_b32_e32 v73, v1
	s_waitcnt lgkmcnt(0)
	v_add_f32_e32 v63, v63, v65
	ds_bpermute_b32 v65, v55, v63
	s_waitcnt lgkmcnt(0)
	v_add_f32_e32 v63, v63, v65
	ds_bpermute_b32 v65, v57, v63
	s_waitcnt lgkmcnt(0)
	v_add_f32_e32 v63, v63, v65
	ds_bpermute_b32 v65, v59, v63
	s_waitcnt lgkmcnt(0)
	v_add_f32_e32 v63, v63, v65
	ds_bpermute_b32 v65, v74, v63
	s_waitcnt lgkmcnt(0)
	v_add_f32_e32 v63, v63, v65
	ds_bpermute_b32 v65, v75, v63
	s_waitcnt lgkmcnt(0)
	v_add_f32_e32 v63, v63, v65
	v_fmamk_f32 v63, v63, 0x3a800000, v162
	v_mul_f32_e32 v65, 0x4b800000, v63
	v_cmp_gt_f32_e32 vcc, s3, v63
	s_nop 1
	v_cndmask_b32_e32 v63, v63, v65, vcc
	v_rsq_f32_e32 v63, v63
	s_nop 0
	v_mul_f32_e32 v65, 0x45800000, v63
	v_cndmask_b32_e32 v94, v63, v65, vcc
	v_pk_mul_f32 v[48:49], v[48:49], v[94:95] op_sel_hi:[1,0]
	v_pk_mul_f32 v[46:47], v[46:47], v[94:95] op_sel_hi:[1,0]
	s_waitcnt vmcnt(11)
	v_pk_mul_f32 v[48:49], v[78:79], v[48:49]
	v_pk_mul_f32 v[46:47], v[76:77], v[46:47]
	s_waitcnt vmcnt(10)
	v_pk_add_f32 v[76:77], v[82:83], 1.0 op_sel_hi:[1,0]
	v_pk_add_f32 v[78:79], v[80:81], 1.0 op_sel_hi:[1,0]
	s_waitcnt vmcnt(9)
	v_pk_fma_f32 v[48:49], v[76:77], v[48:49], v[86:87]
	v_pk_fma_f32 v[46:47], v[78:79], v[46:47], v[84:85]
	v_pk_mul_f32 v[44:45], v[44:45], v[94:95] op_sel_hi:[1,0]
	v_cvt_pk_bf16_f32 v46, v46, v47
	v_cvt_pk_bf16_f32 v47, v48, v49
	global_store_dwordx2 v[92:93], v[46:47], off
	v_pk_mul_f32 v[42:43], v[42:43], v[94:95] op_sel_hi:[1,0]
	v_lshlrev_b32_e32 v46, 2, v56
	v_mov_b32_e32 v47, v1
	v_pk_mul_f32 v[40:41], v[40:41], v[94:95] op_sel_hi:[1,0]
	v_pk_mul_f32 v[38:39], v[38:39], v[94:95] op_sel_hi:[1,0]
	v_pk_mul_f32 v[36:37], v[36:37], v[94:95] op_sel_hi:[1,0]
	v_pk_mul_f32 v[34:35], v[34:35], v[94:95] op_sel_hi:[1,0]
	v_cmp_gt_i32_e32 vcc, s33, v68
	s_waitcnt vmcnt(9)
	v_pk_mul_f32 v[42:43], v[98:99], v[42:43]
	v_pk_mul_f32 v[44:45], v[100:101], v[44:45]
	s_waitcnt vmcnt(8)
	v_pk_add_f32 v[48:49], v[104:105], 1.0 op_sel_hi:[1,0]
	v_pk_add_f32 v[76:77], v[102:103], 1.0 op_sel_hi:[1,0]
	s_waitcnt vmcnt(7)
	v_pk_fma_f32 v[44:45], v[48:49], v[44:45], v[108:109]
	v_pk_fma_f32 v[42:43], v[76:77], v[42:43], v[106:107]
	s_nop 0
	v_cvt_pk_bf16_f32 v42, v42, v43
	v_cvt_pk_bf16_f32 v43, v44, v45
	global_store_dwordx2 v[92:93], v[42:43], off offset:512
	v_lshlrev_b32_e32 v42, 2, v58
	v_mov_b32_e32 v43, v1
	s_waitcnt vmcnt(7)
	v_pk_mul_f32 v[38:39], v[110:111], v[38:39]
	v_pk_mul_f32 v[40:41], v[112:113], v[40:41]
	s_waitcnt vmcnt(6)
	v_pk_add_f32 v[44:45], v[116:117], 1.0 op_sel_hi:[1,0]
	v_pk_add_f32 v[48:49], v[114:115], 1.0 op_sel_hi:[1,0]
	s_waitcnt vmcnt(5)
	v_pk_fma_f32 v[40:41], v[44:45], v[40:41], v[120:121]
	v_pk_fma_f32 v[38:39], v[48:49], v[38:39], v[118:119]
	v_cvt_pk_bf16_f32 v38, v38, v39
	v_cvt_pk_bf16_f32 v39, v40, v41
	global_store_dwordx2 v[92:93], v[38:39], off offset:1024
	s_waitcnt vmcnt(5)
	v_pk_mul_f32 v[34:35], v[34:35], v[122:123]
	v_pk_mul_f32 v[36:37], v[36:37], v[124:125]
	s_waitcnt vmcnt(4)
	v_pk_add_f32 v[38:39], v[128:129], 1.0 op_sel_hi:[1,0]
	v_pk_add_f32 v[40:41], v[126:127], 1.0 op_sel_hi:[1,0]
	s_waitcnt vmcnt(3)
	v_pk_fma_f32 v[36:37], v[36:37], v[38:39], v[132:133]
	v_pk_fma_f32 v[34:35], v[34:35], v[40:41], v[130:131]
	s_nop 0
	v_cvt_pk_bf16_f32 v34, v34, v35
	v_cvt_pk_bf16_f32 v35, v36, v37
	global_store_dwordx2 v[92:93], v[34:35], off offset:1536
	s_and_saveexec_b64 s[4:5], vcc
	s_cbranch_execz .LBB0_1294
	v_lshrrev_b32_e32 v34, 11, v70
	s_movk_i32 s3, 0x1fff
	v_add_u32_e32 v34, 1, v34
	v_cmp_lt_i32_e32 vcc, s3, v68
	v_mov_b32_e32 v80, v23
	v_mov_b32_e32 v81, v19
	v_cndmask_b32_e32 v36, 0, v34, vcc
	v_mov_b64_e32 v[34:35], s[16:17]
	v_mad_u64_u32 v[44:45], s[20:21], v36, s33, v[34:35]
	s_mov_b64 s[20:21], 0x1000
	s_nop 0
	v_lshl_add_u64 v[48:49], v[44:45], 0, s[20:21]
	v_lshl_add_u64 v[38:39], v[48:49], 0, v[0:1]
	global_load_dwordx4 v[34:37], v[52:53], off
	v_lshl_add_u64 v[44:45], v[44:45], 0, v[0:1]
	global_load_dwordx4 v[38:41], v[38:39], off
	v_mov_b32_e32 v70, v22
	global_load_dwordx4 v[76:79], v[44:45], off
	v_lshl_add_u64 v[134:135], v[48:49], 0, v[0:1]
	global_load_dwordx4 v[98:101], v[52:53], off offset:1024
	global_load_dwordx4 v[102:105], v[134:135], off offset:1024
	global_load_dwordx4 v[106:109], v[44:45], off offset:1024
	global_load_dwordx4 v[110:113], v[52:53], off offset:2048
	global_load_dwordx4 v[114:117], v[134:135], off offset:2048
	global_load_dwordx4 v[118:121], v[44:45], off offset:2048
	global_load_dwordx4 v[122:125], v[52:53], off offset:3072
	global_load_dwordx4 v[126:129], v[134:135], off offset:3072
	global_load_dwordx4 v[130:133], v[44:45], off offset:3072
	v_mov_b32_e32 v71, v18
	v_pk_mul_f32 v[80:81], v[80:81], v[80:81]
	v_mov_b32_e32 v82, v31
	v_pk_fma_f32 v[70:71], v[70:71], v[70:71], v[80:81]
	v_mov_b32_e32 v80, v24
	v_mov_b32_e32 v81, v20
	v_pk_fma_f32 v[70:71], v[80:81], v[80:81], v[70:71]
	v_mov_b32_e32 v80, v25
	v_mov_b32_e32 v81, v21
	v_mov_b32_e32 v83, v27
	v_pk_fma_f32 v[70:71], v[80:81], v[80:81], v[70:71]
	v_mov_b32_e32 v80, v30
	v_mov_b32_e32 v81, v26
	v_pk_mul_f32 v[82:83], v[82:83], v[82:83]
	v_add_f32_e32 v63, v70, v71
	v_pk_fma_f32 v[80:81], v[80:81], v[80:81], v[82:83]
	v_mov_b32_e32 v82, v32
	v_mov_b32_e32 v83, v28
	v_pk_fma_f32 v[80:81], v[82:83], v[82:83], v[80:81]
	v_mov_b32_e32 v82, v33
	v_mov_b32_e32 v83, v29
	v_pk_fma_f32 v[80:81], v[82:83], v[82:83], v[80:81]
	s_mov_b32 s3, 0x800000
	v_add_f32_e32 v63, v81, v63
	v_add_f32_e32 v63, v80, v63
	ds_bpermute_b32 v65, v51, v63
	v_ashrrev_i32_e32 v69, 31, v68
	v_lshlrev_b64 v[68:69], 11, v[68:69]
	v_lshl_add_u64 v[80:81], v[60:61], 0, v[68:69]
	s_waitcnt lgkmcnt(0)
	v_add_f32_e32 v63, v63, v65
	ds_bpermute_b32 v65, v55, v63
	s_waitcnt lgkmcnt(0)
	v_add_f32_e32 v63, v63, v65
	ds_bpermute_b32 v65, v57, v63
	s_waitcnt lgkmcnt(0)
	v_add_f32_e32 v63, v63, v65
	ds_bpermute_b32 v65, v59, v63
	s_waitcnt lgkmcnt(0)
	v_add_f32_e32 v63, v63, v65
	ds_bpermute_b32 v65, v74, v63
	s_waitcnt lgkmcnt(0)
	v_add_f32_e32 v63, v63, v65
	ds_bpermute_b32 v65, v75, v63
	s_waitcnt lgkmcnt(0)
	v_add_f32_e32 v63, v63, v65
	v_fmamk_f32 v63, v63, 0x3a800000, v162
	v_mul_f32_e32 v65, 0x4b800000, v63
	v_cmp_gt_f32_e32 vcc, s3, v63
	s_waitcnt vmcnt(10)
	v_pk_add_f32 v[40:41], v[40:41], 1.0 op_sel_hi:[1,0]
	v_cndmask_b32_e32 v63, v63, v65, vcc
	v_rsq_f32_e32 v63, v63
	v_pk_add_f32 v[38:39], v[38:39], 1.0 op_sel_hi:[1,0]
	v_mul_f32_e32 v65, 0x45800000, v63
	v_cndmask_b32_e32 v82, v63, v65, vcc
	v_pk_mul_f32 v[68:69], v[20:21], v[82:83] op_sel_hi:[1,0]
	v_pk_mul_f32 v[70:71], v[18:19], v[82:83] op_sel_hi:[1,0]
	v_pk_mul_f32 v[36:37], v[36:37], v[68:69]
	v_pk_mul_f32 v[34:35], v[34:35], v[70:71]
	s_waitcnt vmcnt(9)
	v_pk_fma_f32 v[36:37], v[40:41], v[36:37], v[78:79]
	v_pk_fma_f32 v[34:35], v[38:39], v[34:35], v[76:77]
	v_cvt_pk_bf16_f32 v34, v34, v35
	v_cvt_pk_bf16_f32 v35, v36, v37
	global_store_dwordx2 v[80:81], v[34:35], off
	v_pk_mul_f32 v[76:77], v[24:25], v[82:83] op_sel_hi:[1,0]
	v_pk_mul_f32 v[78:79], v[22:23], v[82:83] op_sel_hi:[1,0]
	s_waitcnt vmcnt(8)
	v_pk_add_f32 v[40:41], v[104:105], 1.0 op_sel_hi:[1,0]
	v_pk_mul_f32 v[34:35], v[98:99], v[78:79]
	v_pk_mul_f32 v[36:37], v[100:101], v[76:77]
	v_pk_add_f32 v[38:39], v[102:103], 1.0 op_sel_hi:[1,0]
	s_waitcnt vmcnt(7)
	v_pk_fma_f32 v[36:37], v[40:41], v[36:37], v[108:109]
	v_pk_fma_f32 v[34:35], v[38:39], v[34:35], v[106:107]
	v_cvt_pk_bf16_f32 v34, v34, v35
	v_cvt_pk_bf16_f32 v35, v36, v37
	global_store_dwordx2 v[80:81], v[34:35], off offset:512
	v_pk_mul_f32 v[76:77], v[28:29], v[82:83] op_sel_hi:[1,0]
	v_pk_mul_f32 v[78:79], v[26:27], v[82:83] op_sel_hi:[1,0]
	s_waitcnt vmcnt(6)
	v_pk_add_f32 v[40:41], v[116:117], 1.0 op_sel_hi:[1,0]
	v_pk_mul_f32 v[34:35], v[110:111], v[78:79]
	v_pk_mul_f32 v[36:37], v[112:113], v[76:77]
	v_pk_add_f32 v[38:39], v[114:115], 1.0 op_sel_hi:[1,0]
	s_waitcnt vmcnt(5)
	v_pk_fma_f32 v[36:37], v[40:41], v[36:37], v[120:121]
	v_pk_fma_f32 v[34:35], v[38:39], v[34:35], v[118:119]
	v_cvt_pk_bf16_f32 v34, v34, v35
	v_cvt_pk_bf16_f32 v35, v36, v37
	global_store_dwordx2 v[80:81], v[34:35], off offset:1024
	v_pk_mul_f32 v[44:45], v[32:33], v[82:83] op_sel_hi:[1,0]
	v_pk_mul_f32 v[48:49], v[30:31], v[82:83] op_sel_hi:[1,0]
	s_waitcnt vmcnt(4)
	v_pk_add_f32 v[40:41], v[128:129], 1.0 op_sel_hi:[1,0]
	v_pk_mul_f32 v[34:35], v[48:49], v[122:123]
	v_pk_mul_f32 v[36:37], v[44:45], v[124:125]
	v_pk_add_f32 v[38:39], v[126:127], 1.0 op_sel_hi:[1,0]
	s_waitcnt vmcnt(3)
	v_pk_fma_f32 v[36:37], v[36:37], v[40:41], v[132:133]
	v_pk_fma_f32 v[34:35], v[34:35], v[38:39], v[130:131]
	s_nop 0
	v_cvt_pk_bf16_f32 v34, v34, v35
	v_cvt_pk_bf16_f32 v35, v36, v37
	global_store_dwordx2 v[80:81], v[34:35], off offset:1536
.LBB0_1294:
	s_or_b64 exec, exec, s[4:5]
	v_cmp_gt_i32_e32 vcc, s33, v64
	s_and_saveexec_b64 s[4:5], vcc
	s_cbranch_execz .LBB0_1262
	v_lshrrev_b32_e32 v34, 11, v66
	s_movk_i32 s3, 0x1fff
	v_add_u32_e32 v34, 1, v34
	v_cmp_lt_i32_e32 vcc, s3, v64
	v_mov_b32_e32 v76, v11
	v_mov_b32_e32 v77, v15
	v_cndmask_b32_e32 v36, 0, v34, vcc
	v_mov_b64_e32 v[34:35], s[16:17]
	v_mad_u64_u32 v[44:45], s[20:21], v36, s33, v[34:35]
	s_mov_b64 s[20:21], 0x1000
	s_nop 0
	v_lshl_add_u64 v[48:49], v[44:45], 0, s[20:21]
	v_lshl_add_u64 v[38:39], v[48:49], 0, v[0:1]
	global_load_dwordx4 v[34:37], v[52:53], off
	v_lshl_add_u64 v[70:71], v[44:45], 0, v[0:1]
	global_load_dwordx4 v[38:41], v[38:39], off
	v_mov_b32_e32 v44, v10
	global_load_dwordx4 v[66:69], v[70:71], off
	v_lshl_add_u64 v[134:135], v[48:49], 0, v[0:1]
	global_load_dwordx4 v[98:101], v[52:53], off offset:1024
	global_load_dwordx4 v[102:105], v[134:135], off offset:1024
	global_load_dwordx4 v[106:109], v[70:71], off offset:1024
	global_load_dwordx4 v[110:113], v[52:53], off offset:2048
	global_load_dwordx4 v[114:117], v[134:135], off offset:2048
	global_load_dwordx4 v[118:121], v[70:71], off offset:2048
	global_load_dwordx4 v[122:125], v[52:53], off offset:3072
	global_load_dwordx4 v[126:129], v[134:135], off offset:3072
	global_load_dwordx4 v[130:133], v[70:71], off offset:3072
	v_mov_b32_e32 v45, v14
	v_pk_mul_f32 v[76:77], v[76:77], v[76:77]
	s_mov_b32 s3, 0x800000
	v_pk_fma_f32 v[44:45], v[44:45], v[44:45], v[76:77]
	v_mov_b32_e32 v76, v12
	v_mov_b32_e32 v77, v16
	v_pk_fma_f32 v[44:45], v[76:77], v[76:77], v[44:45]
	v_mov_b32_e32 v76, v13
	v_mov_b32_e32 v77, v17
	v_pk_fma_f32 v[44:45], v[76:77], v[76:77], v[44:45]
	v_mov_b32_e32 v76, v3
	v_mov_b32_e32 v77, v7
	v_add_f32_e32 v0, v44, v45
	v_mov_b32_e32 v44, v2
	v_mov_b32_e32 v45, v6
	v_pk_mul_f32 v[76:77], v[76:77], v[76:77]
	v_ashrrev_i32_e32 v65, 31, v64
	v_pk_fma_f32 v[44:45], v[44:45], v[44:45], v[76:77]
	v_mov_b32_e32 v76, v4
	v_mov_b32_e32 v77, v8
	v_pk_fma_f32 v[44:45], v[76:77], v[76:77], v[44:45]
	v_mov_b32_e32 v76, v5
	v_mov_b32_e32 v77, v9
	v_pk_fma_f32 v[44:45], v[76:77], v[76:77], v[44:45]
	v_mov_b32_e32 v73, v1
	v_add_f32_e32 v0, v45, v0
	v_add_f32_e32 v0, v44, v0
	ds_bpermute_b32 v43, v51, v0
	v_lshlrev_b64 v[44:45], 11, v[64:65]
	v_lshl_add_u64 v[76:77], v[60:61], 0, v[44:45]
	v_mov_b32_e32 v47, v1
	s_waitcnt lgkmcnt(0)
	v_add_f32_e32 v0, v0, v43
	ds_bpermute_b32 v43, v55, v0
	s_waitcnt lgkmcnt(0)
	v_add_f32_e32 v0, v0, v43
	ds_bpermute_b32 v43, v57, v0
	s_waitcnt lgkmcnt(0)
	v_add_f32_e32 v0, v0, v43
	ds_bpermute_b32 v43, v59, v0
	s_waitcnt lgkmcnt(0)
	v_add_f32_e32 v0, v0, v43
	ds_bpermute_b32 v43, v74, v0
	s_waitcnt lgkmcnt(0)
	v_add_f32_e32 v0, v0, v43
	ds_bpermute_b32 v43, v75, v0
	s_waitcnt lgkmcnt(0)
	v_add_f32_e32 v0, v0, v43
	v_fmamk_f32 v0, v0, 0x3a800000, v162
	v_mul_f32_e32 v43, 0x4b800000, v0
	v_cmp_gt_f32_e32 vcc, s3, v0
	s_waitcnt vmcnt(10)
	v_pk_add_f32 v[40:41], v[40:41], 1.0 op_sel_hi:[1,0]
	v_cndmask_b32_e32 v0, v0, v43, vcc
	v_rsq_f32_e32 v0, v0
	v_pk_add_f32 v[38:39], v[38:39], 1.0 op_sel_hi:[1,0]
	v_mul_f32_e32 v43, 0x45800000, v0
	v_cndmask_b32_e32 v0, v0, v43, vcc
	v_pk_mul_f32 v[44:45], v[16:17], v[0:1] op_sel_hi:[1,0]
	v_pk_mul_f32 v[64:65], v[14:15], v[0:1] op_sel_hi:[1,0]
	v_pk_mul_f32 v[36:37], v[36:37], v[44:45]
	v_pk_mul_f32 v[34:35], v[34:35], v[64:65]
	s_waitcnt vmcnt(9)
	v_pk_fma_f32 v[36:37], v[40:41], v[36:37], v[68:69]
	v_pk_fma_f32 v[34:35], v[38:39], v[34:35], v[66:67]
	v_cvt_pk_bf16_f32 v34, v34, v35
	v_cvt_pk_bf16_f32 v35, v36, v37
	global_store_dwordx2 v[76:77], v[34:35], off
	v_pk_mul_f32 v[44:45], v[12:13], v[0:1] op_sel_hi:[1,0]
	v_pk_mul_f32 v[68:69], v[10:11], v[0:1] op_sel_hi:[1,0]
	v_mov_b32_e32 v43, v1
	s_waitcnt vmcnt(8)
	v_pk_add_f32 v[40:41], v[104:105], 1.0 op_sel_hi:[1,0]
	v_pk_mul_f32 v[34:35], v[98:99], v[68:69]
	v_pk_mul_f32 v[36:37], v[100:101], v[44:45]
	v_pk_add_f32 v[38:39], v[102:103], 1.0 op_sel_hi:[1,0]
	s_waitcnt vmcnt(7)
	v_pk_fma_f32 v[36:37], v[40:41], v[36:37], v[108:109]
	v_pk_fma_f32 v[34:35], v[38:39], v[34:35], v[106:107]
	v_cvt_pk_bf16_f32 v34, v34, v35
	v_cvt_pk_bf16_f32 v35, v36, v37
	global_store_dwordx2 v[76:77], v[34:35], off offset:512
	v_pk_mul_f32 v[64:65], v[8:9], v[0:1] op_sel_hi:[1,0]
	v_pk_mul_f32 v[66:67], v[6:7], v[0:1] op_sel_hi:[1,0]
	s_waitcnt vmcnt(6)
	v_pk_add_f32 v[40:41], v[116:117], 1.0 op_sel_hi:[1,0]
	v_pk_mul_f32 v[34:35], v[110:111], v[66:67]
	v_pk_mul_f32 v[36:37], v[112:113], v[64:65]
	v_pk_add_f32 v[38:39], v[114:115], 1.0 op_sel_hi:[1,0]
	s_waitcnt vmcnt(5)
	v_pk_fma_f32 v[36:37], v[40:41], v[36:37], v[120:121]
	v_pk_fma_f32 v[34:35], v[38:39], v[34:35], v[118:119]
	v_cvt_pk_bf16_f32 v34, v34, v35
	v_cvt_pk_bf16_f32 v35, v36, v37
	global_store_dwordx2 v[76:77], v[34:35], off offset:1024
	v_pk_mul_f32 v[46:47], v[4:5], v[0:1] op_sel_hi:[1,0]
	v_pk_mul_f32 v[48:49], v[2:3], v[0:1] op_sel_hi:[1,0]
	s_waitcnt vmcnt(4)
	v_pk_add_f32 v[40:41], v[128:129], 1.0 op_sel_hi:[1,0]
	v_pk_mul_f32 v[34:35], v[48:49], v[122:123]
	v_pk_mul_f32 v[36:37], v[46:47], v[124:125]
	v_pk_add_f32 v[38:39], v[126:127], 1.0 op_sel_hi:[1,0]
	s_waitcnt vmcnt(3)
	v_pk_fma_f32 v[36:37], v[36:37], v[40:41], v[132:133]
	v_pk_fma_f32 v[34:35], v[34:35], v[38:39], v[130:131]
	s_nop 0
	v_cvt_pk_bf16_f32 v34, v34, v35
	v_cvt_pk_bf16_f32 v35, v36, v37
	global_store_dwordx2 v[76:77], v[34:35], off offset:1536
	s_branch .LBB0_1262
